# prologue de-serialisation: p->PB conversion with 8 loads in flight for the prompt rows; top-k prefix scan by DPP instead of six ds_bpermute round trips
# baseline (speedup 1.0000x reference)
.LBB0_2504:
	v_readlane_b32 s52, v251, 35
	v_readlane_b32 s53, v251, 36
	v_readlane_b32 s54, v251, 37
	v_readlane_b32 s55, v251, 38
	v_readlane_b32 s64, v251, 47
	v_readlane_b32 s65, v251, 48
	v_readlane_b32 s56, v251, 39
	v_readlane_b32 s57, v251, 40
	v_readlane_b32 s58, v251, 41
	v_readlane_b32 s59, v251, 42
	v_readlane_b32 s60, v251, 43
	v_readlane_b32 s61, v251, 44
	v_readlane_b32 s62, v251, 45
	v_readlane_b32 s63, v251, 46
	v_readlane_b32 s66, v251, 49
	v_readlane_b32 s67, v251, 50
	s_mov_b64 s[52:53], s[64:65]
	s_mov_b64 s[54:55], s[66:67]
	v_readlane_b32 s56, v251, 19
	v_readlane_b32 s57, v251, 20
	v_readlane_b32 s58, v251, 21
	v_readlane_b32 s59, v251, 22
	v_readlane_b32 s60, v251, 23
	v_readlane_b32 s61, v251, 24
	v_readlane_b32 s62, v251, 25
	v_readlane_b32 s63, v251, 26
	v_readlane_b32 s64, v251, 27
	v_readlane_b32 s65, v251, 28
	v_readlane_b32 s4, v252, 7
	v_readlane_b32 s66, v251, 29
	v_readlane_b32 s67, v251, 30
	v_readlane_b32 s68, v251, 31
	v_readlane_b32 s69, v251, 32
	v_readlane_b32 s70, v251, 33
	v_readlane_b32 s71, v251, 34
	s_mov_b64 s[56:57], s[64:65]
	s_and_b64 vcc, exec, s[16:17]
	v_readlane_b32 s5, v252, 8
	v_readlane_b32 s6, v252, 9
	v_readlane_b32 s7, v252, 10
	s_mov_b64 s[58:59], s[66:67]
	s_mov_b64 s[60:61], s[68:69]
	v_readlane_b32 s20, v252, 26
	v_readlane_b32 s21, v252, 24
	s_mov_b64 s[62:63], s[70:71]
	s_cbranch_vccz .LBB0_2554
	v_add_u32_e32 v9, v41, v42
	v_mov_b32_e32 v10, v9
	s_nop 1
	v_add_u32_dpp v10, v10, v10 row_shr:1 row_mask:0xf bank_mask:0xf bound_ctrl:1
	s_nop 1
	v_add_u32_dpp v10, v10, v10 row_shr:2 row_mask:0xf bank_mask:0xf bound_ctrl:1
	s_nop 1
	v_add_u32_dpp v10, v10, v10 row_shr:4 row_mask:0xf bank_mask:0xf bound_ctrl:1
	s_nop 1
	v_add_u32_dpp v10, v10, v10 row_shr:8 row_mask:0xf bank_mask:0xf bound_ctrl:1
	s_nop 1
	v_add_u32_dpp v10, v10, v10 row_bcast:15 row_mask:0xa bank_mask:0xf
	s_nop 1
	v_add_u32_dpp v10, v10, v10 row_bcast:31 row_mask:0xc bank_mask:0xf
	s_nop 1
	v_sub_u32_e32 v9, v10, v9
	v_lshl_add_u32 v40, v9, 2, v138
	v_cmp_le_u32_e32 vcc, s22, v8
	s_and_saveexec_b64 s[0:1], vcc
	ds_write_b32 v40, v11
	v_add_u32_e32 v40, 4, v40
	s_or_b64 exec, exec, s[0:1]
	v_cmp_le_u32_e32 vcc, s22, v1
	s_and_saveexec_b64 s[0:1], vcc
	v_or_b32_e32 v41, 0x40, v11
	ds_write_b32 v40, v41
	v_add_u32_e32 v40, 4, v40
	s_or_b64 exec, exec, s[0:1]
	v_cmp_le_u32_e32 vcc, s22, v2
	s_and_saveexec_b64 s[0:1], vcc
	v_or_b32_e32 v41, 0x80, v11
	ds_write_b32 v40, v41
	v_add_u32_e32 v40, 4, v40
	s_or_b64 exec, exec, s[0:1]
	v_cmp_le_u32_e32 vcc, s22, v3
	s_and_saveexec_b64 s[0:1], vcc
	v_or_b32_e32 v41, 0xc0, v11
	ds_write_b32 v40, v41
	v_add_u32_e32 v40, 4, v40
	s_or_b64 exec, exec, s[0:1]
	v_cmp_le_u32_e32 vcc, s22, v4
	s_and_saveexec_b64 s[0:1], vcc
	v_or_b32_e32 v41, 0x100, v11
	ds_write_b32 v40, v41
	v_add_u32_e32 v40, 4, v40
	s_or_b64 exec, exec, s[0:1]
	v_cmp_le_u32_e32 vcc, s22, v5
	s_and_saveexec_b64 s[0:1], vcc
	v_or_b32_e32 v41, 0x140, v11
	ds_write_b32 v40, v41
	v_add_u32_e32 v40, 4, v40
	s_or_b64 exec, exec, s[0:1]
	v_cmp_le_u32_e32 vcc, s22, v6
	s_and_saveexec_b64 s[0:1], vcc
	v_or_b32_e32 v41, 0x180, v11
	ds_write_b32 v40, v41
	v_add_u32_e32 v40, 4, v40
	s_or_b64 exec, exec, s[0:1]
	v_cmp_le_u32_e32 vcc, s22, v7
	s_and_saveexec_b64 s[0:1], vcc
	v_or_b32_e32 v41, 0x1c0, v11
	ds_write_b32 v40, v41
	v_add_u32_e32 v40, 4, v40
	s_or_b64 exec, exec, s[0:1]
	s_and_b64 vcc, exec, s[14:15]
	s_cbranch_vccnz .Lcmp_c1_g0
	v_cmp_le_u32_e32 vcc, s22, v18
	s_and_saveexec_b64 s[0:1], vcc
	v_or_b32_e32 v41, 0x200, v11
	ds_write_b32 v40, v41
	v_add_u32_e32 v40, 4, v40
	s_or_b64 exec, exec, s[0:1]
	v_cmp_le_u32_e32 vcc, s22, v16
	s_and_saveexec_b64 s[0:1], vcc
	v_or_b32_e32 v41, 0x240, v11
	ds_write_b32 v40, v41
	v_add_u32_e32 v40, 4, v40
	s_or_b64 exec, exec, s[0:1]
	v_cmp_le_u32_e32 vcc, s22, v21
	s_and_saveexec_b64 s[0:1], vcc
	v_or_b32_e32 v41, 0x280, v11
	ds_write_b32 v40, v41
	v_add_u32_e32 v40, 4, v40
	s_or_b64 exec, exec, s[0:1]
	v_cmp_le_u32_e32 vcc, s22, v17
	s_and_saveexec_b64 s[0:1], vcc
	v_or_b32_e32 v41, 0x2c0, v11
	ds_write_b32 v40, v41
	v_add_u32_e32 v40, 4, v40
	s_or_b64 exec, exec, s[0:1]
	v_cmp_le_u32_e32 vcc, s22, v22
	s_and_saveexec_b64 s[0:1], vcc
	v_or_b32_e32 v41, 0x300, v11
	ds_write_b32 v40, v41
	v_add_u32_e32 v40, 4, v40
	s_or_b64 exec, exec, s[0:1]
	v_cmp_le_u32_e32 vcc, s22, v19
	s_and_saveexec_b64 s[0:1], vcc
	v_or_b32_e32 v41, 0x340, v11
	ds_write_b32 v40, v41
	v_add_u32_e32 v40, 4, v40
	s_or_b64 exec, exec, s[0:1]
	v_cmp_le_u32_e32 vcc, s22, v23
	s_and_saveexec_b64 s[0:1], vcc
	v_or_b32_e32 v41, 0x380, v11
	ds_write_b32 v40, v41
	v_add_u32_e32 v40, 4, v40
	s_or_b64 exec, exec, s[0:1]
	v_cmp_le_u32_e32 vcc, s22, v20
	s_and_saveexec_b64 s[0:1], vcc
	v_or_b32_e32 v41, 0x3c0, v11
	ds_write_b32 v40, v41
	v_add_u32_e32 v40, 4, v40
	s_or_b64 exec, exec, s[0:1]

.LBB0_2880:
	v_readlane_b32 s64, v252, 7
	v_readlane_b32 s92, v252, 3
	s_and_b64 vcc, exec, s[42:43]
	v_readlane_b32 s96, v252, 18
	v_readlane_b32 s65, v252, 8
	v_readlane_b32 s66, v252, 9
	v_readlane_b32 s67, v252, 10
	v_readlane_b32 s88, v252, 20
	v_readlane_b32 s68, v251, 51
	v_readlane_b32 s93, v252, 4
	v_readlane_b32 s94, v252, 5
	v_readlane_b32 s95, v252, 6
	v_readlane_b32 s97, v252, 19
	v_readlane_b32 s89, v252, 21
	v_readlane_b32 s69, v251, 52
	v_readlane_b32 s70, v251, 53
	v_readlane_b32 s71, v251, 54
	v_readlane_b32 s72, v251, 55
	v_readlane_b32 s73, v251, 56
	v_readlane_b32 s74, v251, 57
	v_readlane_b32 s75, v251, 58
	v_readlane_b32 s76, v251, 59
	v_readlane_b32 s77, v251, 60
	v_readlane_b32 s78, v251, 61
	v_readlane_b32 s79, v251, 62
	v_readlane_b32 s80, v251, 63
	v_readlane_b32 s81, v252, 0
	v_readlane_b32 s82, v252, 1
	v_readlane_b32 s83, v252, 2
	s_cbranch_vccz .LBB0_2994
	v_add_u32_e32 v37, v84, v76
	v_mov_b32_e32 v38, v37
	s_nop 1
	v_add_u32_dpp v38, v38, v38 row_shr:1 row_mask:0xf bank_mask:0xf bound_ctrl:1
	s_nop 1
	v_add_u32_dpp v38, v38, v38 row_shr:2 row_mask:0xf bank_mask:0xf bound_ctrl:1
	s_nop 1
	v_add_u32_dpp v38, v38, v38 row_shr:4 row_mask:0xf bank_mask:0xf bound_ctrl:1
	s_nop 1
	v_add_u32_dpp v38, v38, v38 row_shr:8 row_mask:0xf bank_mask:0xf bound_ctrl:1
	s_nop 1
	v_add_u32_dpp v38, v38, v38 row_bcast:15 row_mask:0xa bank_mask:0xf
	s_nop 1
	v_add_u32_dpp v38, v38, v38 row_bcast:31 row_mask:0xc bank_mask:0xf
	s_nop 1
	v_sub_u32_e32 v37, v38, v37
	v_lshl_add_u32 v76, v37, 2, v138
	v_cmp_le_u32_e32 vcc, s18, v75
	s_and_saveexec_b64 s[0:1], vcc
	ds_write_b32 v76, v39
	v_add_u32_e32 v76, 4, v76
	s_or_b64 exec, exec, s[0:1]
	v_cmp_le_u32_e32 vcc, s18, v74
	s_and_saveexec_b64 s[0:1], vcc
	v_or_b32_e32 v38, 0x40, v39
	ds_write_b32 v76, v38
	v_add_u32_e32 v76, 4, v76
	s_or_b64 exec, exec, s[0:1]
	v_cmp_le_u32_e32 vcc, s18, v32
	s_and_saveexec_b64 s[0:1], vcc
	v_or_b32_e32 v38, 0x80, v39
	ds_write_b32 v76, v38
	v_add_u32_e32 v76, 4, v76
	s_or_b64 exec, exec, s[0:1]
	v_cmp_le_u32_e32 vcc, s18, v31
	s_and_saveexec_b64 s[0:1], vcc
	v_or_b32_e32 v38, 0xc0, v39
	ds_write_b32 v76, v38
	v_add_u32_e32 v76, 4, v76
	s_or_b64 exec, exec, s[0:1]
	v_cmp_le_u32_e32 vcc, s18, v30
	s_and_saveexec_b64 s[0:1], vcc
	v_or_b32_e32 v38, 0x100, v39
	ds_write_b32 v76, v38
	v_add_u32_e32 v76, 4, v76
	s_or_b64 exec, exec, s[0:1]
	v_cmp_le_u32_e32 vcc, s18, v29
	s_and_saveexec_b64 s[0:1], vcc
	v_or_b32_e32 v38, 0x140, v39
	ds_write_b32 v76, v38
	v_add_u32_e32 v76, 4, v76
	s_or_b64 exec, exec, s[0:1]
	v_cmp_le_u32_e32 vcc, s18, v28
	s_and_saveexec_b64 s[0:1], vcc
	v_or_b32_e32 v38, 0x180, v39
	ds_write_b32 v76, v38
	v_add_u32_e32 v76, 4, v76
	s_or_b64 exec, exec, s[0:1]
	v_cmp_le_u32_e32 vcc, s18, v27
	s_and_saveexec_b64 s[0:1], vcc
	v_or_b32_e32 v38, 0x1c0, v39
	ds_write_b32 v76, v38
	v_add_u32_e32 v76, 4, v76
	s_or_b64 exec, exec, s[0:1]
	v_cmp_le_u32_e32 vcc, s18, v24
	s_and_saveexec_b64 s[0:1], vcc
	v_or_b32_e32 v38, 0x200, v39
	ds_write_b32 v76, v38
	v_add_u32_e32 v76, 4, v76
	s_or_b64 exec, exec, s[0:1]
	v_cmp_le_u32_e32 vcc, s18, v23
	s_and_saveexec_b64 s[0:1], vcc
	v_or_b32_e32 v38, 0x240, v39
	ds_write_b32 v76, v38
	v_add_u32_e32 v76, 4, v76
	s_or_b64 exec, exec, s[0:1]
	v_cmp_le_u32_e32 vcc, s18, v26
	s_and_saveexec_b64 s[0:1], vcc
	v_or_b32_e32 v38, 0x280, v39
	ds_write_b32 v76, v38
	v_add_u32_e32 v76, 4, v76
	s_or_b64 exec, exec, s[0:1]
	v_cmp_le_u32_e32 vcc, s18, v25
	s_and_saveexec_b64 s[0:1], vcc
	v_or_b32_e32 v38, 0x2c0, v39
	ds_write_b32 v76, v38
	v_add_u32_e32 v76, 4, v76
	s_or_b64 exec, exec, s[0:1]
	v_cmp_le_u32_e32 vcc, s18, v22
	s_and_saveexec_b64 s[0:1], vcc
	v_or_b32_e32 v38, 0x300, v39
	ds_write_b32 v76, v38
	v_add_u32_e32 v76, 4, v76
	s_or_b64 exec, exec, s[0:1]
	v_cmp_le_u32_e32 vcc, s18, v21
	s_and_saveexec_b64 s[0:1], vcc
	v_or_b32_e32 v38, 0x340, v39
	ds_write_b32 v76, v38
	v_add_u32_e32 v76, 4, v76
	s_or_b64 exec, exec, s[0:1]
	v_cmp_le_u32_e32 vcc, s18, v20
	s_and_saveexec_b64 s[0:1], vcc
	v_or_b32_e32 v38, 0x380, v39
	ds_write_b32 v76, v38
	v_add_u32_e32 v76, 4, v76
	s_or_b64 exec, exec, s[0:1]
	v_cmp_le_u32_e32 vcc, s18, v19
	s_and_saveexec_b64 s[0:1], vcc
	v_or_b32_e32 v38, 0x3c0, v39
	ds_write_b32 v76, v38
	v_add_u32_e32 v76, 4, v76
	s_or_b64 exec, exec, s[0:1]
	v_cmp_le_u32_e32 vcc, s18, v16
	s_and_saveexec_b64 s[0:1], vcc
	v_or_b32_e32 v38, 0x400, v39
	ds_write_b32 v76, v38
	v_add_u32_e32 v76, 4, v76
	s_or_b64 exec, exec, s[0:1]
	v_cmp_le_u32_e32 vcc, s18, v18
	s_and_saveexec_b64 s[0:1], vcc
	v_or_b32_e32 v38, 0x440, v39
	ds_write_b32 v76, v38
	v_add_u32_e32 v76, 4, v76
	s_or_b64 exec, exec, s[0:1]
	v_cmp_le_u32_e32 vcc, s18, v1
	s_and_saveexec_b64 s[0:1], vcc
	v_or_b32_e32 v38, 0x480, v39
	ds_write_b32 v76, v38
	v_add_u32_e32 v76, 4, v76
	s_or_b64 exec, exec, s[0:1]
	v_cmp_le_u32_e32 vcc, s18, v2
	s_and_saveexec_b64 s[0:1], vcc
	v_or_b32_e32 v38, 0x4c0, v39
	ds_write_b32 v76, v38
	v_add_u32_e32 v76, 4, v76
	s_or_b64 exec, exec, s[0:1]
	v_cmp_le_u32_e32 vcc, s18, v3
	s_and_saveexec_b64 s[0:1], vcc
	v_or_b32_e32 v38, 0x500, v39
	ds_write_b32 v76, v38
	v_add_u32_e32 v76, 4, v76
	s_or_b64 exec, exec, s[0:1]
	v_cmp_le_u32_e32 vcc, s18, v4
	s_and_saveexec_b64 s[0:1], vcc
	v_or_b32_e32 v38, 0x540, v39
	ds_write_b32 v76, v38
	v_add_u32_e32 v76, 4, v76
	s_or_b64 exec, exec, s[0:1]
	v_cmp_le_u32_e32 vcc, s18, v5
	s_and_saveexec_b64 s[0:1], vcc
	v_or_b32_e32 v38, 0x580, v39
	ds_write_b32 v76, v38
	v_add_u32_e32 v76, 4, v76
	s_or_b64 exec, exec, s[0:1]
	v_cmp_le_u32_e32 vcc, s18, v6
	s_and_saveexec_b64 s[0:1], vcc
	v_or_b32_e32 v38, 0x5c0, v39
	ds_write_b32 v76, v38
	v_add_u32_e32 v76, 4, v76
	s_or_b64 exec, exec, s[0:1]
	v_cmp_le_u32_e32 vcc, s18, v7
	s_and_saveexec_b64 s[0:1], vcc
	v_or_b32_e32 v38, 0x600, v39
	ds_write_b32 v76, v38
	v_add_u32_e32 v76, 4, v76
	s_or_b64 exec, exec, s[0:1]
	v_cmp_le_u32_e32 vcc, s18, v8
	s_and_saveexec_b64 s[0:1], vcc
	v_or_b32_e32 v38, 0x640, v39
	ds_write_b32 v76, v38
	v_add_u32_e32 v76, 4, v76
	s_or_b64 exec, exec, s[0:1]
	v_cmp_le_u32_e32 vcc, s18, v9
	s_and_saveexec_b64 s[0:1], vcc
	v_or_b32_e32 v38, 0x680, v39
	ds_write_b32 v76, v38
	v_add_u32_e32 v76, 4, v76
	s_or_b64 exec, exec, s[0:1]
	v_cmp_le_u32_e32 vcc, s18, v10
	s_and_saveexec_b64 s[0:1], vcc
	v_or_b32_e32 v38, 0x6c0, v39
	ds_write_b32 v76, v38
	v_add_u32_e32 v76, 4, v76
	s_or_b64 exec, exec, s[0:1]
	v_cmp_le_u32_e32 vcc, s18, v11
	s_and_saveexec_b64 s[0:1], vcc
	v_or_b32_e32 v38, 0x700, v39
	ds_write_b32 v76, v38
	v_add_u32_e32 v76, 4, v76
	s_or_b64 exec, exec, s[0:1]
	v_cmp_le_u32_e32 vcc, s18, v12
	s_and_saveexec_b64 s[0:1], vcc
	v_or_b32_e32 v38, 0x740, v39
	ds_write_b32 v76, v38
	v_add_u32_e32 v76, 4, v76
	s_or_b64 exec, exec, s[0:1]
	v_cmp_le_u32_e32 vcc, s18, v13
	s_and_saveexec_b64 s[0:1], vcc
	v_or_b32_e32 v38, 0x780, v39
	ds_write_b32 v76, v38
	v_add_u32_e32 v76, 4, v76
	s_or_b64 exec, exec, s[0:1]
	v_cmp_le_u32_e32 vcc, s18, v14
	s_and_saveexec_b64 s[0:1], vcc
	v_or_b32_e32 v38, 0x7c0, v39
	ds_write_b32 v76, v38
	v_add_u32_e32 v76, 4, v76
	s_or_b64 exec, exec, s[0:1]
	v_cmp_le_u32_e32 vcc, s18, v15
	s_and_saveexec_b64 s[0:1], vcc
	v_or_b32_e32 v38, 0x800, v39
	ds_write_b32 v76, v38
	v_add_u32_e32 v76, 4, v76
	s_or_b64 exec, exec, s[0:1]
	v_cmp_le_u32_e32 vcc, s18, v34
	s_and_saveexec_b64 s[0:1], vcc
	v_or_b32_e32 v38, 0x840, v39
	ds_write_b32 v76, v38
	v_add_u32_e32 v76, 4, v76
	s_or_b64 exec, exec, s[0:1]
	v_cmp_le_u32_e32 vcc, s18, v33
	s_and_saveexec_b64 s[0:1], vcc
	v_or_b32_e32 v38, 0x880, v39
	ds_write_b32 v76, v38
	v_add_u32_e32 v76, 4, v76
	s_or_b64 exec, exec, s[0:1]
	v_cmp_le_u32_e32 vcc, s18, v36
	s_and_saveexec_b64 s[0:1], vcc
	v_or_b32_e32 v38, 0x8c0, v39
	ds_write_b32 v76, v38
	v_add_u32_e32 v76, 4, v76
	s_or_b64 exec, exec, s[0:1]
	v_cmp_le_u32_e32 vcc, s18, v35
	s_and_saveexec_b64 s[0:1], vcc
	v_or_b32_e32 v38, 0x900, v39
	ds_write_b32 v76, v38
	v_add_u32_e32 v76, 4, v76
	s_or_b64 exec, exec, s[0:1]
	v_cmp_le_u32_e32 vcc, s18, v17
	s_and_saveexec_b64 s[0:1], vcc
	v_or_b32_e32 v38, 0x940, v39
	ds_write_b32 v76, v38
	v_add_u32_e32 v76, 4, v76
	s_or_b64 exec, exec, s[0:1]
	v_cmp_le_u32_e32 vcc, s18, v50
	s_and_saveexec_b64 s[0:1], vcc
	v_or_b32_e32 v38, 0x980, v39
	ds_write_b32 v76, v38
	v_add_u32_e32 v76, 4, v76
	s_or_b64 exec, exec, s[0:1]
	v_cmp_le_u32_e32 vcc, s18, v47
	s_and_saveexec_b64 s[0:1], vcc
	v_or_b32_e32 v38, 0x9c0, v39
	ds_write_b32 v76, v38
	v_add_u32_e32 v76, 4, v76
	s_or_b64 exec, exec, s[0:1]
	s_and_b64 vcc, exec, s[14:15]
	s_cbranch_vccnz .Lcmp_c2_g0
	v_cmp_le_u32_e32 vcc, s18, v52
	s_and_saveexec_b64 s[0:1], vcc
	v_or_b32_e32 v38, 0xa00, v39
	ds_write_b32 v76, v38
	v_add_u32_e32 v76, 4, v76
	s_or_b64 exec, exec, s[0:1]
	v_cmp_le_u32_e32 vcc, s18, v49
	s_and_saveexec_b64 s[0:1], vcc
	v_or_b32_e32 v38, 0xa40, v39
	ds_write_b32 v76, v38
	v_add_u32_e32 v76, 4, v76
	s_or_b64 exec, exec, s[0:1]
	v_cmp_le_u32_e32 vcc, s18, v54
	s_and_saveexec_b64 s[0:1], vcc
	v_or_b32_e32 v38, 0xa80, v39
	ds_write_b32 v76, v38
	v_add_u32_e32 v76, 4, v76
	s_or_b64 exec, exec, s[0:1]
	v_cmp_le_u32_e32 vcc, s18, v51
	s_and_saveexec_b64 s[0:1], vcc
	v_or_b32_e32 v38, 0xac0, v39
	ds_write_b32 v76, v38
	v_add_u32_e32 v76, 4, v76
	s_or_b64 exec, exec, s[0:1]
	v_cmp_le_u32_e32 vcc, s18, v56
	s_and_saveexec_b64 s[0:1], vcc
	v_or_b32_e32 v38, 0xb00, v39
	ds_write_b32 v76, v38
	v_add_u32_e32 v76, 4, v76
	s_or_b64 exec, exec, s[0:1]
	v_cmp_le_u32_e32 vcc, s18, v53
	s_and_saveexec_b64 s[0:1], vcc
	v_or_b32_e32 v38, 0xb40, v39
	ds_write_b32 v76, v38
	v_add_u32_e32 v76, 4, v76
	s_or_b64 exec, exec, s[0:1]
	v_cmp_le_u32_e32 vcc, s18, v57
	s_and_saveexec_b64 s[0:1], vcc
	v_or_b32_e32 v38, 0xb80, v39
	ds_write_b32 v76, v38
	v_add_u32_e32 v76, 4, v76
	s_or_b64 exec, exec, s[0:1]
	v_cmp_le_u32_e32 vcc, s18, v55
	s_and_saveexec_b64 s[0:1], vcc
	v_or_b32_e32 v38, 0xbc0, v39
	ds_write_b32 v76, v38
	v_add_u32_e32 v76, 4, v76
	s_or_b64 exec, exec, s[0:1]
